# s_setprio 1 for blocks >= 256 also in the even_b and even_d item loops
# baseline (speedup 1.0000x reference)
; DI int vblock() { const int G = gridDim.x, b = blockIdx.x; return ((G & 7) == 0) ? (b & 7) * (G >> 3) + (b >> 3) : b; }
; DI void phase_even_b(const Ctx& c, int l, bf16* lds) {
;   float* rs = (float*)(lds + GEMM_LDS_BF16);
;   const int qrows = (l == 0) ? MT : MLAT;
;   const int n_q = (qrows / 128) * 6, n_k = 132 * 4, n_v = 132 * 4, n_g1 = 8 * 132;
;   const int total = n_q + n_k + n_v + n_g1;
;   for (int it0 = vblock(); it0 < total; it0 += gridDim.x) {
;     const int it = (it0 < n_g1) ? (n_q + n_k + n_v + it0) : (it0 - n_g1);
.Lsy5_done:
.LBB0_568:
	s_or_b64 exec, exec, s[0:1]
	s_cmp_eq_u32 s86, 0
	s_cselect_b64 s[16:17], -1, 0
	s_and_b64 s[0:1], s[16:17], exec
	s_movk_i32 s0, 0x318
	s_cselect_b32 s15, s0, 0x300
	s_or_b32 s18, s15, 0x840
	v_readlane_b32 s0, v253, 60
	s_cmp_ge_i32 s0, s18
	s_waitcnt lgkmcnt(0)
	s_barrier
	s_cbranch_scc1 .LBB0_737
	s_add_i32 s19, s15, 0x210
	s_or_b32 s20, s15, 0x420
	v_readlane_b32 s21, v253, 60
	v_readlane_b32 vcc_lo, v252, 32
	s_cmp_ge_u32 vcc_lo, 0x10000
	s_cbranch_scc0 .Lpr_b
	s_setprio 1
.Lpr_b:
	s_branch .LBB0_571
.LBB0_570:
	s_add_i32 s21, s21, s40
	s_cmp_ge_i32 s21, s18
	s_cbranch_scc1 .LBB0_737

; DI int otid() { int t = threadIdx.x; asm volatile("" : "+v"(t)); return t; }
; DI float bf2f(bf16 v) { return __uint_as_float(((unsigned)v) << 16); }
;   DI float* TAB() const { return (float*)(p.ws + WS_TAB); }
;   DI bf16* P() const { return (bf16*)(p.ws + WS_P); }
;   DI bf16* K() const { return (bf16*)(p.ws + WS_K); }
; DI RowPos row_pos(int m) { RowPos r; r.lat = m < MLAT; if (r.lat) { r.b = m >> 13; r.pos = m & 8191; } else { const int mc = m - MLAT; r.b = mc >> 8; r.pos = mc & 255; } return r; }
; DI void phase_even_b(const Ctx& c, int l, bf16* lds) {
;     ...
;   const size_t gt = (size_t)blockIdx.x * NT + otid(), gs = (size_t)gridDim.x * NT;
;   for (size_t i = gt; i < (size_t)MT * 16; i += gs) {
;     const int row = (int)(i >> 4), f = (int)(i & 15);
;     const bf16* kr = c.P() + (size_t)row * LDP + C_KR;
;     const float x1 = bf2f(kr[f]), x2 = bf2f(kr[16 + f]);
;     const RowPos rp = row_pos(row); const int pos = rp.lat ? L + rp.pos : rp.pos;
;     float cs = 1.f, sn = 0.f;
;     if (rp.lat) { cs = c.TAB()[TB_ROPE + (rp.pos * 16 + f) * 2]; sn = c.TAB()[TB_ROPE + (rp.pos * 16 + f) * 2 + 1]; }
;     const unsigned o = pk2(x1 * cs - x2 * sn, x1 * sn + x2 * cs);
;     for (int h = 0; h < 8; ++h) *(unsigned*)(c.K() + ((size_t)(rp.b * 8 + h) * T + pos) * 96 + 64 + 2 * f) = o;
;   }
.LBB0_737:
	s_setprio 0
	v_mov_b32_e32 v4, v172
	v_readlane_b32 s0, v252, 33
	v_readlane_b32 s1, v252, 34
	v_ashrrev_i32_e32 v5, 31, v4
	s_nop 0
	v_lshl_add_u64 v[2:3], s[0:1], 0, v[4:5]
	s_mov_b64 s[0:1], 0x42000
	v_cmp_gt_u64_e32 vcc, s[0:1], v[2:3]
	s_and_saveexec_b64 s[4:5], vcc
	s_cbranch_execz .LBB0_742
	v_and_b32_e32 v0, 15, v4
	v_lshlrev_b32_e32 v4, 1, v0
	s_mov_b64 s[6:7], 0
	v_lshlrev_b32_e32 v0, 1, v0
	s_branch .LBB0_740

; DI float silu(float x) { return x * __builtin_amdgcn_rcpf(1.f + __expf(-x)); }
;   DI bf16* HY() const { return (bf16*)(p.ws + WS_HY); }
;   DI bf16* P() const { return (bf16*)(p.ws + WS_P); }
; DI int vblock() { const int G = gridDim.x, b = blockIdx.x; return ((G & 7) == 0) ? (b & 7) * (G >> 3) + (b >> 3) : b; }
; DI u32x2 pk4(f32x4 v) { return u32x2{pk2(v[0], v[1]), pk2(v[2], v[3])}; }
; DI f32x4 unpk4(u32x2 u) { return f32x4{__uint_as_float(u[0] << 16), __uint_as_float(u[0] & 0xffff0000u), __uint_as_float(u[1] << 16), __uint_as_float(u[1] & 0xffff0000u)}; }
; DI void attn_item(const Ctx& c, int item, bf16* lds) {
;     ...
; #pragma unroll
;   for (int qs = 0; qs < 2; ++qs) {
;     const float inv = 1.f / xhalf_sum(lsum[qs]);
;     const int row = rowbase + wave * 64 + qs * 32 + r;
;     const bf16* mg = c.P() + (size_t)row * LDP + C_MG + h * 64;
;     bf16* dst = c.HY() + (size_t)row * D + 512 + h * 64;
; #pragma unroll
;     for (int vt = 0; vt < 2; ++vt)
; #pragma unroll
;       for (int g = 0; g < 4; ++g) {
;         const int vd = 32 * vt + 8 * g + 4 * hh;
;         const f32x4 g4 = unpk4(*(const u32x2*)(mg + vd));
;         f32x4 o = {ot[qs][vt][4 * g] * inv * silu(g4[0]), ot[qs][vt][4 * g + 1] * inv * silu(g4[1]), ot[qs][vt][4 * g + 2] * inv * silu(g4[2]), ot[qs][vt][4 * g + 3] * inv * silu(g4[3])};
;         *(u32x2*)(dst + vd) = pk4(o);
;       }
; DI void phase_even_d(const Ctx& c, int l, bf16* lds) {
;   const int n_ctx = (l == 0 ? 16 : 0), n_g3 = 8 * ((l == 0) ? 132 : 128);
;   for (int it = vblock(); it < n_ctx + n_g3; it += gridDim.x) {
;     if (it < n_ctx) attn_item(c, 512 + it, lds);
.LBB0_882:
	s_or_b64 exec, exec, s[0:1]
	s_and_b64 s[0:1], s[16:17], exec
	s_movk_i32 s0, 0x430
	s_cselect_b32 s1, s0, 0x400
	v_readlane_b32 s0, v253, 60
	v_writelane_b32 v254, s1, 59
	s_cmp_ge_i32 s0, s1
	s_waitcnt lgkmcnt(0)
	s_barrier
	s_cbranch_scc1 .LBB0_1022
	s_and_b64 s[0:1], s[16:17], exec
	v_readlane_b32 s0, v254, 49
	v_readlane_b32 s1, v254, 50
	s_cselect_b32 s18, 16, 0
	s_lshl_b32 s1, s0, 9
	s_lshl_b32 s84, s0, 7
	v_readlane_b32 s44, v252, 16
	v_writelane_b32 v254, s1, 60
	s_lshl_b64 s[0:1], s[84:85], 2
	v_readlane_b32 s50, v252, 22
	v_readlane_b32 s51, v252, 23
	s_add_u32 s0, s50, s0
	s_addc_u32 s1, s51, s1
	s_and_b64 s[4:5], s[16:17], exec
	v_writelane_b32 v254, s0, 61
	s_movk_i32 s4, 0x84
	v_readlane_b32 s45, v252, 17
	v_writelane_b32 v254, s1, 62
	s_cselect_b32 s0, s4, 0x80
	v_cvt_f32_ubyte0_e32 v159, s0
	v_rcp_iflag_f32_e32 v161, v159
	v_writelane_b32 v254, s0, 63
	v_readlane_b32 s0, v253, 60
	s_mov_b32 s84, s0
	v_writelane_b32 v255, s18, 0
	v_readlane_b32 s46, v252, 18
	v_readlane_b32 s47, v252, 19
	v_readlane_b32 s48, v252, 20
	v_readlane_b32 s49, v252, 21
	v_readlane_b32 s52, v252, 24
	v_readlane_b32 s53, v252, 25
	v_readlane_b32 s54, v252, 26
	v_readlane_b32 s55, v252, 27
	v_readlane_b32 s56, v252, 28
	v_readlane_b32 s57, v252, 29
	v_readlane_b32 s58, v252, 30
	v_readlane_b32 s59, v252, 31
	v_readlane_b32 vcc_lo, v252, 32
	s_cmp_ge_u32 vcc_lo, 0x10000
	s_cbranch_scc0 .Lpr_d
	s_setprio 1
.Lpr_d:
	s_branch .LBB0_886
.LBB0_884:
	v_mov_b32_e32 v0, v206
	s_nop 1
	v_permlane32_swap_b32_e32 v206, v0
	v_add_f32_e32 v0, v206, v0
	v_div_scale_f32 v66, s[4:5], v0, v0, 1.0
	v_rcp_f32_e32 v67, v66
	v_add_u32_e32 v70, s11, v163
	s_movk_i32 s0, 0xf400
	v_mov_b32_e32 v163, v1
	v_fma_f32 v68, -v66, v67, 1.0
	v_fmac_f32_e32 v67, v68, v67
	v_div_scale_f32 v68, vcc, 1.0, v0, 1.0
	v_mul_f32_e32 v69, v68, v67
	v_fma_f32 v71, -v66, v69, v68
	v_fmac_f32_e32 v69, v71, v67
	v_fma_f32 v66, -v66, v69, v68
	v_div_fmas_f32 v66, v66, v67, v69
	v_div_fixup_f32 v0, v66, v0, 1.0
	v_mov_b64_e32 v[66:67], s[88:89]
	v_mad_i64_i32 v[68:69], s[4:5], v70, s78, v[66:67]
	s_lshl_b32 s4, s10, 7
	s_and_b32 s4, s4, 0x380
	s_mov_b32 s5, s85
	v_lshl_add_u64 v[72:73], v[68:69], 0, s[4:5]
	v_mad_i64_i32 v[68:69], s[6:7], v70, s0, v[68:69]
	v_lshl_add_u64 v[72:73], v[72:73], 0, v[162:163]
	s_mov_b64 s[2:3], 0x3228f80
	v_lshl_add_u64 v[74:75], v[68:69], 0, s[4:5]
	v_lshl_add_u64 v[68:69], v[72:73], 0, s[2:3]
	v_add_co_u32_e32 v72, vcc, s81, v72
	s_nop 1
	v_addc_co_u32_e32 v73, vcc, 0, v73, vcc
	s_barrier
	global_load_dwordx2 v[72:73], v[72:73], off offset:3968
	v_pk_mul_f32 v[50:51], v[50:51], v[0:1] op_sel_hi:[1,0]
	v_pk_mul_f32 v[52:53], v[52:53], v[0:1] op_sel_hi:[1,0]
	s_mov_b64 s[8:9], 0x1128400
	s_mov_b32 s1, 0x1128000
	v_pk_mul_f32 v[54:55], v[54:55], v[0:1] op_sel_hi:[1,0]
	v_pk_mul_f32 v[56:57], v[56:57], v[0:1] op_sel_hi:[1,0]
	v_pk_mul_f32 v[58:59], v[58:59], v[0:1] op_sel_hi:[1,0]
	v_pk_mul_f32 v[34:35], v[34:35], v[0:1] op_sel_hi:[1,0]
	v_pk_mul_f32 v[36:37], v[36:37], v[0:1] op_sel_hi:[1,0]
	v_pk_mul_f32 v[38:39], v[38:39], v[0:1] op_sel_hi:[1,0]
	v_pk_mul_f32 v[40:41], v[40:41], v[0:1] op_sel_hi:[1,0]
	s_waitcnt vmcnt(0)
	v_lshlrev_b32_e32 v76, 16, v72
	v_mul_f32_e32 v71, 0xbfb8aa3b, v76
	v_exp_f32_e32 v71, v71
	v_and_b32_e32 v77, 0xffff0000, v72
	v_add_f32_e32 v71, 1.0, v71
	v_rcp_f32_e32 v78, v71
	v_mul_f32_e32 v71, 0xbfb8aa3b, v77
	v_exp_f32_e32 v71, v71
	s_nop 0
	v_add_f32_e32 v71, 1.0, v71
	v_rcp_f32_e32 v79, v71
	s_nop 0
	v_pk_mul_f32 v[76:77], v[78:79], v[76:77]
	s_nop 0
	v_pk_mul_f32 v[50:51], v[50:51], v[76:77]
	s_nop 0
	v_cvt_pk_bf16_f32 v72, v50, v51
	v_lshlrev_b32_e32 v50, 16, v73
	v_mul_f32_e32 v71, 0xbfb8aa3b, v50
	v_exp_f32_e32 v71, v71
	v_and_b32_e32 v51, 0xffff0000, v73
	v_add_f32_e32 v71, 1.0, v71
	v_rcp_f32_e32 v76, v71
	v_mul_f32_e32 v71, 0xbfb8aa3b, v51
	v_exp_f32_e32 v71, v71
	s_nop 0
	v_add_f32_e32 v71, 1.0, v71
	v_rcp_f32_e32 v77, v71
	s_nop 0
	v_pk_mul_f32 v[50:51], v[76:77], v[50:51]
	s_nop 0
	v_pk_mul_f32 v[50:51], v[52:53], v[50:51]
	v_lshl_add_u64 v[52:53], v[74:75], 0, v[162:163]
	v_cvt_pk_bf16_f32 v73, v50, v51
	v_lshl_add_u64 v[50:51], v[52:53], 0, s[8:9]
	v_add_co_u32_e32 v52, vcc, s1, v52
	s_nop 1
	v_addc_co_u32_e32 v53, vcc, 0, v53, vcc
	global_store_dwordx2 v[52:53], v[72:73], off offset:1024
	global_load_dwordx2 v[52:53], v[68:69], off offset:16
	s_waitcnt vmcnt(0)
	v_lshlrev_b32_e32 v72, 16, v52
	v_and_b32_e32 v73, 0xffff0000, v52
	v_mul_f32_e32 v52, 0xbfb8aa3b, v72
	v_exp_f32_e32 v52, v52
	s_nop 0
	v_add_f32_e32 v52, 1.0, v52
	v_rcp_f32_e32 v74, v52
	v_mul_f32_e32 v52, 0xbfb8aa3b, v73
	v_exp_f32_e32 v52, v52
	s_nop 0
	v_add_f32_e32 v52, 1.0, v52
	v_rcp_f32_e32 v75, v52
	s_nop 0
	v_pk_mul_f32 v[72:73], v[74:75], v[72:73]
	s_nop 0
	v_pk_mul_f32 v[54:55], v[54:55], v[72:73]
	s_nop 0
	v_cvt_pk_bf16_f32 v52, v54, v55
	v_lshlrev_b32_e32 v54, 16, v53
	v_and_b32_e32 v55, 0xffff0000, v53
	v_mul_f32_e32 v53, 0xbfb8aa3b, v54
	v_exp_f32_e32 v53, v53
	s_nop 0
	v_add_f32_e32 v53, 1.0, v53
	v_rcp_f32_e32 v72, v53
	v_mul_f32_e32 v53, 0xbfb8aa3b, v55
	v_exp_f32_e32 v53, v53
	s_nop 0
	v_add_f32_e32 v53, 1.0, v53
	v_rcp_f32_e32 v73, v53
	s_nop 0
	v_pk_mul_f32 v[54:55], v[72:73], v[54:55]
	s_nop 0
	v_pk_mul_f32 v[54:55], v[56:57], v[54:55]
	s_nop 0
	v_cvt_pk_bf16_f32 v53, v54, v55
	global_store_dwordx2 v[50:51], v[52:53], off offset:16
	global_load_dwordx2 v[52:53], v[68:69], off offset:32
	s_waitcnt vmcnt(0)
; DI float silu(float x) { return x * __builtin_amdgcn_rcpf(1.f + __expf(-x)); }
; DI u32x2 pk4(f32x4 v) { return u32x2{pk2(v[0], v[1]), pk2(v[2], v[3])}; }
; DI f32x4 unpk4(u32x2 u) { return f32x4{__uint_as_float(u[0] << 16), __uint_as_float(u[0] & 0xffff0000u), __uint_as_float(u[1] << 16), __uint_as_float(u[1] & 0xffff0000u)}; }
; DI void attn_item(const Ctx& c, int item, bf16* lds) {
;     ...
; #pragma unroll
;     for (int vt = 0; vt < 2; ++vt)
; #pragma unroll
;       for (int g = 0; g < 4; ++g) {
;         const int vd = 32 * vt + 8 * g + 4 * hh;
;         const f32x4 g4 = unpk4(*(const u32x2*)(mg + vd));
;         f32x4 o = {ot[qs][vt][4 * g] * inv * silu(g4[0]), ot[qs][vt][4 * g + 1] * inv * silu(g4[1]), ot[qs][vt][4 * g + 2] * inv * silu(g4[2]), ot[qs][vt][4 * g + 3] * inv * silu(g4[3])};
;         *(u32x2*)(dst + vd) = pk4(o);
;       }
	v_lshlrev_b32_e32 v54, 16, v52
	v_and_b32_e32 v55, 0xffff0000, v52
	v_mul_f32_e32 v52, 0xbfb8aa3b, v54
	v_exp_f32_e32 v52, v52
	s_nop 0
	v_add_f32_e32 v52, 1.0, v52
	v_rcp_f32_e32 v56, v52
	v_mul_f32_e32 v52, 0xbfb8aa3b, v55
	v_exp_f32_e32 v52, v52
	s_nop 0
	v_add_f32_e32 v52, 1.0, v52
	v_rcp_f32_e32 v57, v52
	s_nop 0
	v_pk_mul_f32 v[54:55], v[56:57], v[54:55]
	s_nop 0
	v_pk_mul_f32 v[54:55], v[58:59], v[54:55]
	v_pk_mul_f32 v[58:59], v[60:61], v[0:1] op_sel_hi:[1,0]
	v_cvt_pk_bf16_f32 v52, v54, v55
	v_lshlrev_b32_e32 v54, 16, v53
	v_and_b32_e32 v55, 0xffff0000, v53
	v_mul_f32_e32 v53, 0xbfb8aa3b, v54
	v_exp_f32_e32 v53, v53
	s_nop 0
	v_add_f32_e32 v53, 1.0, v53
	v_rcp_f32_e32 v56, v53
	v_mul_f32_e32 v53, 0xbfb8aa3b, v55
	v_exp_f32_e32 v53, v53
	s_nop 0
	v_add_f32_e32 v53, 1.0, v53
	v_rcp_f32_e32 v57, v53
	s_nop 0
	v_pk_mul_f32 v[54:55], v[56:57], v[54:55]
	s_nop 0
	v_pk_mul_f32 v[54:55], v[58:59], v[54:55]
	v_pk_mul_f32 v[58:59], v[62:63], v[0:1] op_sel_hi:[1,0]
	v_cvt_pk_bf16_f32 v53, v54, v55
	global_store_dwordx2 v[50:51], v[52:53], off offset:32
	global_load_dwordx2 v[52:53], v[68:69], off offset:48
	s_waitcnt vmcnt(0)
	v_lshlrev_b32_e32 v54, 16, v52
	v_and_b32_e32 v55, 0xffff0000, v52
	v_mul_f32_e32 v52, 0xbfb8aa3b, v54
	v_exp_f32_e32 v52, v52
	s_nop 0
	v_add_f32_e32 v52, 1.0, v52
	v_rcp_f32_e32 v56, v52
	v_mul_f32_e32 v52, 0xbfb8aa3b, v55
	v_exp_f32_e32 v52, v52
	s_nop 0
	v_add_f32_e32 v52, 1.0, v52
	v_rcp_f32_e32 v57, v52
	s_nop 0
	v_pk_mul_f32 v[54:55], v[56:57], v[54:55]
	s_nop 0
	v_pk_mul_f32 v[54:55], v[58:59], v[54:55]
	v_pk_mul_f32 v[58:59], v[64:65], v[0:1] op_sel_hi:[1,0]
	v_cvt_pk_bf16_f32 v52, v54, v55
	v_lshlrev_b32_e32 v54, 16, v53
	v_and_b32_e32 v55, 0xffff0000, v53
	v_mul_f32_e32 v53, 0xbfb8aa3b, v54
	v_exp_f32_e32 v53, v53
	s_nop 0
	v_add_f32_e32 v53, 1.0, v53
	v_rcp_f32_e32 v56, v53
	v_mul_f32_e32 v53, 0xbfb8aa3b, v55
	v_exp_f32_e32 v53, v53
	s_nop 0
	v_add_f32_e32 v53, 1.0, v53
	v_rcp_f32_e32 v57, v53
	s_nop 0
	v_pk_mul_f32 v[54:55], v[56:57], v[54:55]
	s_nop 0
	v_pk_mul_f32 v[54:55], v[58:59], v[54:55]
	s_nop 0
	v_cvt_pk_bf16_f32 v53, v54, v55
	global_store_dwordx2 v[50:51], v[52:53], off offset:48
	global_load_dwordx2 v[52:53], v[68:69], off offset:64
	s_waitcnt vmcnt(0)
	v_lshlrev_b32_e32 v54, 16, v52
	v_and_b32_e32 v55, 0xffff0000, v52
	v_mul_f32_e32 v52, 0xbfb8aa3b, v54
	v_exp_f32_e32 v52, v52
	s_nop 0
	v_add_f32_e32 v52, 1.0, v52
	v_rcp_f32_e32 v56, v52
	v_mul_f32_e32 v52, 0xbfb8aa3b, v55
	v_exp_f32_e32 v52, v52
	s_nop 0
	v_add_f32_e32 v52, 1.0, v52
	v_rcp_f32_e32 v57, v52
	v_lshlrev_b32_e32 v52, 16, v53
	v_and_b32_e32 v53, 0xffff0000, v53
	v_pk_mul_f32 v[54:55], v[56:57], v[54:55]
	s_nop 0
	v_pk_mul_f32 v[34:35], v[34:35], v[54:55]
	s_nop 0
	v_cvt_pk_bf16_f32 v34, v34, v35
	v_mul_f32_e32 v35, 0xbfb8aa3b, v52
	v_exp_f32_e32 v35, v35
	s_nop 0
	v_add_f32_e32 v35, 1.0, v35
	v_rcp_f32_e32 v54, v35
	v_mul_f32_e32 v35, 0xbfb8aa3b, v53
	v_exp_f32_e32 v35, v35
	s_nop 0
	v_add_f32_e32 v35, 1.0, v35
	v_rcp_f32_e32 v55, v35
	s_nop 0
	v_pk_mul_f32 v[52:53], v[54:55], v[52:53]
	s_nop 0
	v_pk_mul_f32 v[36:37], v[36:37], v[52:53]
	s_nop 0
	v_cvt_pk_bf16_f32 v35, v36, v37
	global_store_dwordx2 v[50:51], v[34:35], off offset:64
	global_load_dwordx2 v[34:35], v[68:69], off offset:80
	s_waitcnt vmcnt(0)
	v_lshlrev_b32_e32 v36, 16, v34
	v_and_b32_e32 v37, 0xffff0000, v34
	v_mul_f32_e32 v34, 0xbfb8aa3b, v36
	v_exp_f32_e32 v34, v34
	s_nop 0
	v_add_f32_e32 v34, 1.0, v34
	v_rcp_f32_e32 v52, v34
	v_mul_f32_e32 v34, 0xbfb8aa3b, v37
	v_exp_f32_e32 v34, v34
	s_nop 0
	v_add_f32_e32 v34, 1.0, v34
	v_rcp_f32_e32 v53, v34
	s_nop 0
	v_pk_mul_f32 v[36:37], v[52:53], v[36:37]
	s_nop 0
	v_pk_mul_f32 v[36:37], v[38:39], v[36:37]
	s_nop 0
	v_cvt_pk_bf16_f32 v34, v36, v37
	v_lshlrev_b32_e32 v36, 16, v35
	v_and_b32_e32 v37, 0xffff0000, v35
	v_mul_f32_e32 v35, 0xbfb8aa3b, v36
	v_exp_f32_e32 v35, v35
	s_nop 0
	v_add_f32_e32 v35, 1.0, v35
	v_rcp_f32_e32 v38, v35
	v_mul_f32_e32 v35, 0xbfb8aa3b, v37
	v_exp_f32_e32 v35, v35
	s_nop 0
	v_add_f32_e32 v35, 1.0, v35
	v_rcp_f32_e32 v39, v35
	s_nop 0
	v_pk_mul_f32 v[36:37], v[38:39], v[36:37]
	s_nop 0
	v_pk_mul_f32 v[36:37], v[40:41], v[36:37]
	v_pk_mul_f32 v[40:41], v[42:43], v[0:1] op_sel_hi:[1,0]
	v_cvt_pk_bf16_f32 v35, v36, v37
	global_store_dwordx2 v[50:51], v[34:35], off offset:80
	global_load_dwordx2 v[34:35], v[68:69], off offset:96
	s_waitcnt vmcnt(0)
	v_lshlrev_b32_e32 v36, 16, v34
	v_and_b32_e32 v37, 0xffff0000, v34
	v_mul_f32_e32 v34, 0xbfb8aa3b, v36
	v_exp_f32_e32 v34, v34
	s_nop 0
	v_add_f32_e32 v34, 1.0, v34
	v_rcp_f32_e32 v38, v34
	v_mul_f32_e32 v34, 0xbfb8aa3b, v37
	v_exp_f32_e32 v34, v34
	s_nop 0
	v_add_f32_e32 v34, 1.0, v34
	v_rcp_f32_e32 v39, v34
	s_nop 0
	v_pk_mul_f32 v[36:37], v[38:39], v[36:37]
	s_nop 0
	v_pk_mul_f32 v[36:37], v[40:41], v[36:37]
	v_pk_mul_f32 v[40:41], v[44:45], v[0:1] op_sel_hi:[1,0]
	v_cvt_pk_bf16_f32 v34, v36, v37
	v_lshlrev_b32_e32 v36, 16, v35
	v_and_b32_e32 v37, 0xffff0000, v35
	v_mul_f32_e32 v35, 0xbfb8aa3b, v36
	v_exp_f32_e32 v35, v35
	s_nop 0
	v_add_f32_e32 v35, 1.0, v35
	v_rcp_f32_e32 v38, v35
	v_mul_f32_e32 v35, 0xbfb8aa3b, v37
	v_exp_f32_e32 v35, v35
	s_nop 0
	v_add_f32_e32 v35, 1.0, v35
	v_rcp_f32_e32 v39, v35
	s_nop 0
	v_pk_mul_f32 v[36:37], v[38:39], v[36:37]
	s_nop 0
	v_pk_mul_f32 v[36:37], v[40:41], v[36:37]
	v_pk_mul_f32 v[40:41], v[46:47], v[0:1] op_sel_hi:[1,0]
	v_cvt_pk_bf16_f32 v35, v36, v37
	global_store_dwordx2 v[50:51], v[34:35], off offset:96
	global_load_dwordx2 v[34:35], v[68:69], off offset:112
	s_waitcnt vmcnt(0)
; DI float silu(float x) { return x * __builtin_amdgcn_rcpf(1.f + __expf(-x)); }
;   DI bf16* HY() const { return (bf16*)(p.ws + WS_HY); }
;   DI bf16* P() const { return (bf16*)(p.ws + WS_P); }
; DI u32x2 pk4(f32x4 v) { return u32x2{pk2(v[0], v[1]), pk2(v[2], v[3])}; }
; DI f32x4 unpk4(u32x2 u) { return f32x4{__uint_as_float(u[0] << 16), __uint_as_float(u[0] & 0xffff0000u), __uint_as_float(u[1] << 16), __uint_as_float(u[1] & 0xffff0000u)}; }
; DI void attn_item(const Ctx& c, int item, bf16* lds) {
;     ...
; #pragma unroll
;   for (int qs = 0; qs < 2; ++qs) {
;     const float inv = 1.f / xhalf_sum(lsum[qs]);
;     const int row = rowbase + wave * 64 + qs * 32 + r;
;     const bf16* mg = c.P() + (size_t)row * LDP + C_MG + h * 64;
;     bf16* dst = c.HY() + (size_t)row * D + 512 + h * 64;
; #pragma unroll
;     for (int vt = 0; vt < 2; ++vt)
; #pragma unroll
;       for (int g = 0; g < 4; ++g) {
;         const int vd = 32 * vt + 8 * g + 4 * hh;
;         const f32x4 g4 = unpk4(*(const u32x2*)(mg + vd));
;         f32x4 o = {ot[qs][vt][4 * g] * inv * silu(g4[0]), ot[qs][vt][4 * g + 1] * inv * silu(g4[1]), ot[qs][vt][4 * g + 2] * inv * silu(g4[2]), ot[qs][vt][4 * g + 3] * inv * silu(g4[3])};
;         *(u32x2*)(dst + vd) = pk4(o);
;       }
	v_lshlrev_b32_e32 v36, 16, v34
	v_and_b32_e32 v37, 0xffff0000, v34
	v_mul_f32_e32 v34, 0xbfb8aa3b, v36
	v_exp_f32_e32 v34, v34
	s_nop 0
	v_add_f32_e32 v34, 1.0, v34
	v_rcp_f32_e32 v38, v34
	v_mul_f32_e32 v34, 0xbfb8aa3b, v37
	v_exp_f32_e32 v34, v34
	s_nop 0
	v_add_f32_e32 v34, 1.0, v34
	v_rcp_f32_e32 v39, v34
	s_nop 0
	v_pk_mul_f32 v[36:37], v[38:39], v[36:37]
	s_nop 0
	v_pk_mul_f32 v[36:37], v[40:41], v[36:37]
	v_pk_mul_f32 v[40:41], v[48:49], v[0:1] op_sel_hi:[1,0]
	v_cvt_pk_bf16_f32 v34, v36, v37
	v_lshlrev_b32_e32 v36, 16, v35
	v_and_b32_e32 v37, 0xffff0000, v35
	v_mul_f32_e32 v35, 0xbfb8aa3b, v36
	v_mul_f32_e32 v0, 0xbfb8aa3b, v37
	v_exp_f32_e32 v35, v35
	v_exp_f32_e32 v0, v0
	v_add_f32_e32 v35, 1.0, v35
	v_add_f32_e32 v0, 1.0, v0
	v_rcp_f32_e32 v38, v35
	v_rcp_f32_e32 v39, v0
	v_mov_b32_e32 v0, v108
	s_nop 1
	v_permlane32_swap_b32_e32 v108, v0
	v_pk_mul_f32 v[36:37], v[38:39], v[36:37]
	v_add_f32_e32 v0, v108, v0
	v_pk_mul_f32 v[36:37], v[40:41], v[36:37]
	s_nop 0
	v_cvt_pk_bf16_f32 v35, v36, v37
	global_store_dwordx2 v[50:51], v[34:35], off offset:112
	v_div_scale_f32 v34, s[6:7], v0, v0, 1.0
	v_rcp_f32_e32 v35, v34
	s_nop 0
	v_fma_f32 v36, -v34, v35, 1.0
	v_fmac_f32_e32 v35, v36, v35
	v_div_scale_f32 v36, vcc, 1.0, v0, 1.0
	v_mul_f32_e32 v37, v36, v35
	v_fma_f32 v38, -v34, v37, v36
	v_fmac_f32_e32 v37, v38, v35
	v_fma_f32 v34, -v34, v37, v36
	v_div_fmas_f32 v34, v34, v35, v37
	v_add_u32_e32 v38, 32, v70
	v_div_fixup_f32 v0, v34, v0, 1.0
	v_mad_i64_i32 v[34:35], s[6:7], v38, s78, v[66:67]
	v_lshl_add_u64 v[36:37], v[34:35], 0, s[4:5]
	v_mad_i64_i32 v[34:35], s[6:7], v38, s0, v[34:35]
	v_lshl_add_u64 v[36:37], v[36:37], 0, v[162:163]
	v_lshl_add_u64 v[38:39], v[34:35], 0, s[4:5]
	v_lshl_add_u64 v[34:35], v[36:37], 0, s[2:3]
	v_add_co_u32_e32 v36, vcc, s81, v36
	v_pk_mul_f32 v[18:19], v[18:19], v[0:1] op_sel_hi:[1,0]
	s_nop 0
	v_addc_co_u32_e32 v37, vcc, 0, v37, vcc
	global_load_dwordx2 v[36:37], v[36:37], off offset:3968
	v_pk_mul_f32 v[20:21], v[20:21], v[0:1] op_sel_hi:[1,0]
	v_pk_mul_f32 v[22:23], v[22:23], v[0:1] op_sel_hi:[1,0]
	v_pk_mul_f32 v[24:25], v[24:25], v[0:1] op_sel_hi:[1,0]
	v_pk_mul_f32 v[26:27], v[26:27], v[0:1] op_sel_hi:[1,0]
	v_pk_mul_f32 v[2:3], v[2:3], v[0:1] op_sel_hi:[1,0]
	v_pk_mul_f32 v[4:5], v[4:5], v[0:1] op_sel_hi:[1,0]
	v_pk_mul_f32 v[6:7], v[6:7], v[0:1] op_sel_hi:[1,0]
	v_pk_mul_f32 v[8:9], v[8:9], v[0:1] op_sel_hi:[1,0]
	s_waitcnt vmcnt(0)
	v_lshlrev_b32_e32 v40, 16, v36
	v_and_b32_e32 v41, 0xffff0000, v36
	v_mul_f32_e32 v36, 0xbfb8aa3b, v40
	v_exp_f32_e32 v36, v36
	s_nop 0
	v_add_f32_e32 v36, 1.0, v36
	v_rcp_f32_e32 v42, v36
	v_mul_f32_e32 v36, 0xbfb8aa3b, v41
	v_exp_f32_e32 v36, v36
	s_nop 0
	v_add_f32_e32 v36, 1.0, v36
	v_rcp_f32_e32 v43, v36
	s_nop 0
	v_pk_mul_f32 v[40:41], v[42:43], v[40:41]
	s_nop 0
	v_pk_mul_f32 v[18:19], v[18:19], v[40:41]
	s_nop 0
	v_cvt_pk_bf16_f32 v36, v18, v19
	v_lshlrev_b32_e32 v18, 16, v37
	v_and_b32_e32 v19, 0xffff0000, v37
	v_mul_f32_e32 v37, 0xbfb8aa3b, v18
	v_exp_f32_e32 v37, v37
	s_nop 0
	v_add_f32_e32 v37, 1.0, v37
	v_rcp_f32_e32 v40, v37
	v_mul_f32_e32 v37, 0xbfb8aa3b, v19
	v_exp_f32_e32 v37, v37
	s_nop 0
	v_add_f32_e32 v37, 1.0, v37
	v_rcp_f32_e32 v41, v37
	s_nop 0
	v_pk_mul_f32 v[18:19], v[40:41], v[18:19]
	s_nop 0
	v_pk_mul_f32 v[18:19], v[20:21], v[18:19]
	v_lshl_add_u64 v[20:21], v[38:39], 0, v[162:163]
	v_cvt_pk_bf16_f32 v37, v18, v19
	v_lshl_add_u64 v[18:19], v[20:21], 0, s[8:9]
	v_add_co_u32_e32 v20, vcc, s1, v20
	s_nop 1
	v_addc_co_u32_e32 v21, vcc, 0, v21, vcc
	global_store_dwordx2 v[20:21], v[36:37], off offset:1024
	global_load_dwordx2 v[20:21], v[34:35], off offset:16
	s_waitcnt vmcnt(0)
	v_lshlrev_b32_e32 v36, 16, v20
	v_and_b32_e32 v37, 0xffff0000, v20
	v_mul_f32_e32 v20, 0xbfb8aa3b, v36
	v_exp_f32_e32 v20, v20
	s_nop 0
	v_add_f32_e32 v20, 1.0, v20
	v_rcp_f32_e32 v38, v20
	v_mul_f32_e32 v20, 0xbfb8aa3b, v37
	v_exp_f32_e32 v20, v20
	s_nop 0
	v_add_f32_e32 v20, 1.0, v20
	v_rcp_f32_e32 v39, v20
	s_nop 0
	v_pk_mul_f32 v[36:37], v[38:39], v[36:37]
	s_nop 0
	v_pk_mul_f32 v[22:23], v[22:23], v[36:37]
	s_nop 0
	v_cvt_pk_bf16_f32 v20, v22, v23
	v_lshlrev_b32_e32 v22, 16, v21
	v_and_b32_e32 v23, 0xffff0000, v21
	v_mul_f32_e32 v21, 0xbfb8aa3b, v22
	v_exp_f32_e32 v21, v21
	s_nop 0
	v_add_f32_e32 v21, 1.0, v21
	v_rcp_f32_e32 v36, v21
	v_mul_f32_e32 v21, 0xbfb8aa3b, v23
	v_exp_f32_e32 v21, v21
	s_nop 0
	v_add_f32_e32 v21, 1.0, v21
	v_rcp_f32_e32 v37, v21
	s_nop 0
	v_pk_mul_f32 v[22:23], v[36:37], v[22:23]
	s_nop 0
	v_pk_mul_f32 v[22:23], v[24:25], v[22:23]
	s_nop 0
	v_cvt_pk_bf16_f32 v21, v22, v23
	global_store_dwordx2 v[18:19], v[20:21], off offset:16
	global_load_dwordx2 v[20:21], v[34:35], off offset:32
	s_waitcnt vmcnt(0)
	v_lshlrev_b32_e32 v22, 16, v20
	v_and_b32_e32 v23, 0xffff0000, v20
	v_mul_f32_e32 v20, 0xbfb8aa3b, v22
	v_exp_f32_e32 v20, v20
	s_nop 0
	v_add_f32_e32 v20, 1.0, v20
	v_rcp_f32_e32 v24, v20
	v_mul_f32_e32 v20, 0xbfb8aa3b, v23
	v_exp_f32_e32 v20, v20
	s_nop 0
	v_add_f32_e32 v20, 1.0, v20
	v_rcp_f32_e32 v25, v20
	s_nop 0
	v_pk_mul_f32 v[22:23], v[24:25], v[22:23]
	s_nop 0
	v_pk_mul_f32 v[22:23], v[26:27], v[22:23]
	v_pk_mul_f32 v[26:27], v[28:29], v[0:1] op_sel_hi:[1,0]
	v_cvt_pk_bf16_f32 v20, v22, v23
	v_lshlrev_b32_e32 v22, 16, v21
	v_and_b32_e32 v23, 0xffff0000, v21
	v_mul_f32_e32 v21, 0xbfb8aa3b, v22
	v_exp_f32_e32 v21, v21
	s_nop 0
	v_add_f32_e32 v21, 1.0, v21
	v_rcp_f32_e32 v24, v21
	v_mul_f32_e32 v21, 0xbfb8aa3b, v23
	v_exp_f32_e32 v21, v21
	s_nop 0
	v_add_f32_e32 v21, 1.0, v21
	v_rcp_f32_e32 v25, v21
	s_nop 0
	v_pk_mul_f32 v[22:23], v[24:25], v[22:23]
	s_nop 0
	v_pk_mul_f32 v[22:23], v[26:27], v[22:23]
	v_pk_mul_f32 v[26:27], v[30:31], v[0:1] op_sel_hi:[1,0]
	v_cvt_pk_bf16_f32 v21, v22, v23
	global_store_dwordx2 v[18:19], v[20:21], off offset:32
	global_load_dwordx2 v[20:21], v[34:35], off offset:48
	s_waitcnt vmcnt(0)
; DI float silu(float x) { return x * __builtin_amdgcn_rcpf(1.f + __expf(-x)); }
; DI u32x2 pk4(f32x4 v) { return u32x2{pk2(v[0], v[1]), pk2(v[2], v[3])}; }
; DI f32x4 unpk4(u32x2 u) { return f32x4{__uint_as_float(u[0] << 16), __uint_as_float(u[0] & 0xffff0000u), __uint_as_float(u[1] << 16), __uint_as_float(u[1] & 0xffff0000u)}; }
; DI void attn_item(const Ctx& c, int item, bf16* lds) {
;     ...
; #pragma unroll
;     for (int vt = 0; vt < 2; ++vt)
; #pragma unroll
;       for (int g = 0; g < 4; ++g) {
;         const int vd = 32 * vt + 8 * g + 4 * hh;
;         const f32x4 g4 = unpk4(*(const u32x2*)(mg + vd));
;         f32x4 o = {ot[qs][vt][4 * g] * inv * silu(g4[0]), ot[qs][vt][4 * g + 1] * inv * silu(g4[1]), ot[qs][vt][4 * g + 2] * inv * silu(g4[2]), ot[qs][vt][4 * g + 3] * inv * silu(g4[3])};
;         *(u32x2*)(dst + vd) = pk4(o);
;       }
	v_lshlrev_b32_e32 v22, 16, v20
	v_and_b32_e32 v23, 0xffff0000, v20
	v_mul_f32_e32 v20, 0xbfb8aa3b, v22
	v_exp_f32_e32 v20, v20
	s_nop 0
	v_add_f32_e32 v20, 1.0, v20
	v_rcp_f32_e32 v24, v20
	v_mul_f32_e32 v20, 0xbfb8aa3b, v23
	v_exp_f32_e32 v20, v20
	s_nop 0
	v_add_f32_e32 v20, 1.0, v20
	v_rcp_f32_e32 v25, v20
	s_nop 0
	v_pk_mul_f32 v[22:23], v[24:25], v[22:23]
	s_nop 0
	v_pk_mul_f32 v[22:23], v[26:27], v[22:23]
	v_pk_mul_f32 v[26:27], v[32:33], v[0:1] op_sel_hi:[1,0]
	v_cvt_pk_bf16_f32 v20, v22, v23
	v_lshlrev_b32_e32 v22, 16, v21
	v_and_b32_e32 v23, 0xffff0000, v21
	v_mul_f32_e32 v21, 0xbfb8aa3b, v22
	v_exp_f32_e32 v21, v21
	s_nop 0
	v_add_f32_e32 v21, 1.0, v21
	v_rcp_f32_e32 v24, v21
	v_mul_f32_e32 v21, 0xbfb8aa3b, v23
	v_exp_f32_e32 v21, v21
	s_nop 0
	v_add_f32_e32 v21, 1.0, v21
	v_rcp_f32_e32 v25, v21
	s_nop 0
	v_pk_mul_f32 v[22:23], v[24:25], v[22:23]
	s_nop 0
	v_pk_mul_f32 v[22:23], v[26:27], v[22:23]
	s_nop 0
	v_cvt_pk_bf16_f32 v21, v22, v23
	global_store_dwordx2 v[18:19], v[20:21], off offset:48
	global_load_dwordx2 v[20:21], v[34:35], off offset:64
	s_waitcnt vmcnt(0)
	v_lshlrev_b32_e32 v22, 16, v20
	v_and_b32_e32 v23, 0xffff0000, v20
	v_mul_f32_e32 v20, 0xbfb8aa3b, v22
	v_exp_f32_e32 v20, v20
	s_nop 0
	v_add_f32_e32 v20, 1.0, v20
	v_rcp_f32_e32 v24, v20
	v_mul_f32_e32 v20, 0xbfb8aa3b, v23
	v_exp_f32_e32 v20, v20
	s_nop 0
	v_add_f32_e32 v20, 1.0, v20
	v_rcp_f32_e32 v25, v20
	v_lshlrev_b32_e32 v20, 16, v21
	v_and_b32_e32 v21, 0xffff0000, v21
	v_pk_mul_f32 v[22:23], v[24:25], v[22:23]
	s_nop 0
	v_pk_mul_f32 v[2:3], v[2:3], v[22:23]
	s_nop 0
	v_cvt_pk_bf16_f32 v2, v2, v3
	v_mul_f32_e32 v3, 0xbfb8aa3b, v20
	v_exp_f32_e32 v3, v3
	s_nop 0
	v_add_f32_e32 v3, 1.0, v3
	v_rcp_f32_e32 v22, v3
	v_mul_f32_e32 v3, 0xbfb8aa3b, v21
	v_exp_f32_e32 v3, v3
	s_nop 0
	v_add_f32_e32 v3, 1.0, v3
	v_rcp_f32_e32 v23, v3
	s_nop 0
	v_pk_mul_f32 v[20:21], v[22:23], v[20:21]
	s_nop 0
	v_pk_mul_f32 v[4:5], v[4:5], v[20:21]
	s_nop 0
	v_cvt_pk_bf16_f32 v3, v4, v5
	global_store_dwordx2 v[18:19], v[2:3], off offset:64
	global_load_dwordx2 v[2:3], v[34:35], off offset:80
	s_waitcnt vmcnt(0)
	v_lshlrev_b32_e32 v4, 16, v2
	v_and_b32_e32 v5, 0xffff0000, v2
	v_mul_f32_e32 v2, 0xbfb8aa3b, v4
	v_exp_f32_e32 v2, v2
	s_nop 0
	v_add_f32_e32 v2, 1.0, v2
	v_rcp_f32_e32 v20, v2
	v_mul_f32_e32 v2, 0xbfb8aa3b, v5
	v_exp_f32_e32 v2, v2
	s_nop 0
	v_add_f32_e32 v2, 1.0, v2
	v_rcp_f32_e32 v21, v2
	s_nop 0
	v_pk_mul_f32 v[4:5], v[20:21], v[4:5]
	s_nop 0
	v_pk_mul_f32 v[4:5], v[6:7], v[4:5]
	s_nop 0
	v_cvt_pk_bf16_f32 v2, v4, v5
	v_lshlrev_b32_e32 v4, 16, v3
	v_and_b32_e32 v5, 0xffff0000, v3
	v_mul_f32_e32 v3, 0xbfb8aa3b, v4
	v_exp_f32_e32 v3, v3
	s_nop 0
	v_add_f32_e32 v3, 1.0, v3
	v_rcp_f32_e32 v6, v3
	v_mul_f32_e32 v3, 0xbfb8aa3b, v5
	v_exp_f32_e32 v3, v3
	s_nop 0
	v_add_f32_e32 v3, 1.0, v3
	v_rcp_f32_e32 v7, v3
	s_nop 0
	v_pk_mul_f32 v[4:5], v[6:7], v[4:5]
	s_nop 0
	v_pk_mul_f32 v[4:5], v[8:9], v[4:5]
	v_pk_mul_f32 v[8:9], v[10:11], v[0:1] op_sel_hi:[1,0]
	v_cvt_pk_bf16_f32 v3, v4, v5
	global_store_dwordx2 v[18:19], v[2:3], off offset:80
	global_load_dwordx2 v[2:3], v[34:35], off offset:96
	s_waitcnt vmcnt(0)
	v_lshlrev_b32_e32 v4, 16, v2
	v_and_b32_e32 v5, 0xffff0000, v2
	v_mul_f32_e32 v2, 0xbfb8aa3b, v4
	v_exp_f32_e32 v2, v2
	s_nop 0
	v_add_f32_e32 v2, 1.0, v2
	v_rcp_f32_e32 v6, v2
	v_mul_f32_e32 v2, 0xbfb8aa3b, v5
	v_exp_f32_e32 v2, v2
	s_nop 0
	v_add_f32_e32 v2, 1.0, v2
	v_rcp_f32_e32 v7, v2
	s_nop 0
	v_pk_mul_f32 v[4:5], v[6:7], v[4:5]
	s_nop 0
	v_pk_mul_f32 v[4:5], v[8:9], v[4:5]
	v_pk_mul_f32 v[8:9], v[12:13], v[0:1] op_sel_hi:[1,0]
	v_cvt_pk_bf16_f32 v2, v4, v5
	v_lshlrev_b32_e32 v4, 16, v3
	v_and_b32_e32 v5, 0xffff0000, v3
	v_mul_f32_e32 v3, 0xbfb8aa3b, v4
	v_exp_f32_e32 v3, v3
	s_nop 0
	v_add_f32_e32 v3, 1.0, v3
	v_rcp_f32_e32 v6, v3
	v_mul_f32_e32 v3, 0xbfb8aa3b, v5
	v_exp_f32_e32 v3, v3
	s_nop 0
	v_add_f32_e32 v3, 1.0, v3
	v_rcp_f32_e32 v7, v3
	s_nop 0
	v_pk_mul_f32 v[4:5], v[6:7], v[4:5]
	s_nop 0
	v_pk_mul_f32 v[4:5], v[8:9], v[4:5]
	v_pk_mul_f32 v[8:9], v[14:15], v[0:1] op_sel_hi:[1,0]
	v_cvt_pk_bf16_f32 v3, v4, v5
	global_store_dwordx2 v[18:19], v[2:3], off offset:96
	global_load_dwordx2 v[2:3], v[34:35], off offset:112
	s_waitcnt vmcnt(0)
	v_lshlrev_b32_e32 v4, 16, v2
	v_and_b32_e32 v5, 0xffff0000, v2
	v_mul_f32_e32 v2, 0xbfb8aa3b, v4
	v_exp_f32_e32 v2, v2
	s_nop 0
	v_add_f32_e32 v2, 1.0, v2
	v_rcp_f32_e32 v6, v2
	v_mul_f32_e32 v2, 0xbfb8aa3b, v5
	v_exp_f32_e32 v2, v2
	s_nop 0
	v_add_f32_e32 v2, 1.0, v2
	v_rcp_f32_e32 v7, v2
	s_nop 0
	v_pk_mul_f32 v[4:5], v[6:7], v[4:5]
	s_nop 0
	v_pk_mul_f32 v[4:5], v[8:9], v[4:5]
	v_pk_mul_f32 v[8:9], v[16:17], v[0:1] op_sel_hi:[1,0]
	v_cvt_pk_bf16_f32 v2, v4, v5
	v_lshlrev_b32_e32 v4, 16, v3
	v_and_b32_e32 v5, 0xffff0000, v3
	v_mul_f32_e32 v3, 0xbfb8aa3b, v4
	v_mul_f32_e32 v0, 0xbfb8aa3b, v5
	v_exp_f32_e32 v3, v3
	v_exp_f32_e32 v0, v0
	v_add_f32_e32 v3, 1.0, v3
	v_add_f32_e32 v0, 1.0, v0
	v_rcp_f32_e32 v6, v3
	v_rcp_f32_e32 v7, v0
	s_nop 0
	v_pk_mul_f32 v[4:5], v[6:7], v[4:5]
	s_nop 0
	v_pk_mul_f32 v[4:5], v[8:9], v[4:5]
	s_nop 0
	v_cvt_pk_bf16_f32 v3, v4, v5
	global_store_dwordx2 v[18:19], v[2:3], off offset:112

; DI int vblock() { const int G = gridDim.x, b = blockIdx.x; return ((G & 7) == 0) ? (b & 7) * (G >> 3) + (b >> 3) : b; }
; DI void phase_even_d(const Ctx& c, int l, bf16* lds) {
;     ...
;   for (int it = vblock(); it < n_ctx + n_g3; it += gridDim.x) {
;     if (it < n_ctx) attn_item(c, 512 + it, lds);
;     else gla_g3_item(c, l, it - n_ctx, lds);
;   }
; }
.LBB0_1021:
	s_setprio 0
	v_readlane_b32 s90, v254, 9
	v_readlane_b32 s92, v254, 11
	v_readlane_b32 s94, v254, 13
	v_readlane_b32 s52, v254, 15
	v_readlane_b32 s44, v254, 18
	v_readlane_b32 s56, v254, 20
	v_readlane_b32 s48, v254, 22
	v_readlane_b32 s34, v254, 25
	v_readlane_b32 s58, v254, 27
	v_readlane_b32 s91, v254, 10
	v_readlane_b32 s93, v254, 12
	v_readlane_b32 s95, v254, 14
	v_readlane_b32 s53, v254, 16
	v_readlane_b32 s45, v254, 19
	v_readlane_b32 s57, v254, 21
	v_readlane_b32 s49, v254, 23
	v_readlane_b32 s41, v254, 24
	v_readlane_b32 s35, v254, 26
	v_readlane_b32 s59, v254, 28
	s_mov_b64 s[46:47], 0xc080
	s_mov_b64 s[36:37], 0xc180
	s_mov_b64 s[38:39], 0x4ffff
	s_mov_b64 s[42:43], 0xc0
	s_mov_b64 s[50:51], 0x30000
	s_mov_b64 s[54:55], 0x20080
